# attention tile loop: cross-half exchange by v_permlane32_swap instead of ds_bpermute (no LDS round trip), bit-identical
# speedup vs baseline: 1.0135x; 1.0135x over previous
; __device__ __forceinline__ float softplusf_(float z) { return fmaxf(z, 0.f) + __logf(1.f + __expf(-fabsf(z))); }
; __global__ void __launch_bounds__(NTHR, 2) fwd_kernel(Args args) {
;     ...
;                         bf16x8 kf2[4], va2[2][2];
;                         ATT_LOAD(kf2, va2, kt > 1 ? kt - 2 : 0);
;                         f32x16 Sx;
; #pragma unroll
;                         for (int i = 0; i < 16; ++i) Sx[i] = 0.f;
; #pragma unroll
;                         for (int d0 = 0; d0 < 4; ++d0) Sx = __builtin_amdgcn_mfma_f32_32x32x16_bf16(kf[d0], qr[d0], Sx, 0, 0, 0);
;                         const bool diag = (kt == qb);
;                         float lk[16];
; #pragma unroll
;                         for (int i = 0; i < 16; ++i) { const bool valid = !diag || (16 * hh + i < r); const float z = Sx[i]; const float sp = softplusf_(z);
;                             lk[i] = valid ? -sp : 0.f; Sx[i] = valid ? z - sp : -1e30f; }
.LBB0_171:
	v_mov_b64_e32 v[34:35], v[94:95]
	v_mov_b64_e32 v[94:95], v[32:33]
	v_lshl_add_u64 v[32:33], v[34:35], 1, v[92:93]
	s_mov_b32 s2, 0x80000
	v_add_co_u32_e32 v36, vcc, s2, v32
	s_cmp_lg_u32 s4, 0
	s_nop 0
	v_addc_co_u32_e32 v37, vcc, 0, v33, vcc
	global_load_dwordx4 v[64:67], v[36:37], off offset:16
	global_load_dwordx4 v[68:71], v[32:33], off offset:16
	global_load_dwordx4 v[72:75], v[36:37], off
	global_load_dwordx4 v[76:79], v[32:33], off
	v_lshlrev_b64 v[32:33], 11, v[34:35]
	v_lshl_add_u64 v[32:33], v[90:91], 0, v[32:33]
	global_load_dwordx4 v[96:99], v[32:33], off offset:96
	global_load_dwordx4 v[100:103], v[32:33], off offset:64
	global_load_dwordx4 v[104:107], v[32:33], off offset:32
	s_nop 0
	global_load_dwordx4 v[32:35], v[32:33], off
	s_cselect_b64 s[2:3], -1, 0
	s_or_b64 vcc, s[2:3], s[38:39]
	s_waitcnt vmcnt(0)
	v_mfma_f32_32x32x16_bf16 v[32:47], v[32:35], v[48:51], 0
	v_mfma_f32_32x32x16_bf16 v[32:47], v[104:107], v[52:55], v[32:47]
	v_mfma_f32_32x32x16_bf16 v[32:47], v[100:103], v[56:59], v[32:47]
	v_mfma_f32_32x32x16_bf16 v[32:47], v[96:99], v[60:63], v[32:47]
	s_nop 11
	v_mul_f32_e64 v96, |v32|, s79
	v_exp_f32_e32 v96, v96
	v_max_f32_e32 v89, v32, v32
	v_max_f32_e32 v89, 0, v89
	v_add_f32_e32 v96, 1.0, v96
	v_cmp_gt_f32_e64 s[70:71], s33, v96
	s_nop 1
	v_cndmask_b32_e64 v97, 0, 32, s[70:71]
	v_ldexp_f32 v96, v96, v97
	v_log_f32_e32 v96, v96
	s_nop 0
	v_mul_f32_e32 v97, 0x3f317217, v96
	v_fma_f32 v97, v96, s96, -v97
	v_fmac_f32_e32 v97, 0x3377d1cf, v96
	v_fmac_f32_e32 v97, 0x3f317217, v96
	v_cmp_lt_f32_e64 s[74:75], |v96|, s97
	s_nop 1
	v_cndmask_b32_e64 v96, v96, v97, s[74:75]
	v_cndmask_b32_e64 v97, 0, v199, s[70:71]
	v_sub_f32_e32 v96, v96, v97
	v_mul_f32_e64 v97, |v33|, s79
	v_exp_f32_e32 v97, v97
	v_add_f32_e32 v96, v89, v96
	v_cndmask_b32_e64 v89, 0, -v96, vcc
	v_sub_f32_e32 v32, v32, v96
	v_add_f32_e32 v97, 1.0, v97
	v_cmp_gt_f32_e64 s[70:71], s33, v97
	v_max_f32_e32 v96, v33, v33
	v_max_f32_e32 v96, 0, v96
	v_cndmask_b32_e64 v98, 0, 32, s[70:71]
	v_ldexp_f32 v97, v97, v98
	v_log_f32_e32 v97, v97
	v_cndmask_b32_e32 v32, v200, v32, vcc
	s_or_b64 vcc, s[2:3], s[40:41]
	v_mul_f32_e32 v98, 0x3f317217, v97
	v_fma_f32 v98, v97, s96, -v98
	v_fmac_f32_e32 v98, 0x3377d1cf, v97
	v_fmac_f32_e32 v98, 0x3f317217, v97
	v_cmp_lt_f32_e64 s[74:75], |v97|, s97
	s_nop 1
	v_cndmask_b32_e64 v97, v97, v98, s[74:75]
	v_cndmask_b32_e64 v98, 0, v199, s[70:71]
	v_sub_f32_e32 v97, v97, v98
	v_mul_f32_e64 v98, |v34|, s79
	v_exp_f32_e32 v98, v98
	v_add_f32_e32 v97, v96, v97
	v_cndmask_b32_e64 v96, 0, -v97, vcc
	v_sub_f32_e32 v33, v33, v97
	v_add_f32_e32 v98, 1.0, v98
	v_cmp_gt_f32_e64 s[70:71], s33, v98
	v_max_f32_e32 v97, v34, v34
	v_max_f32_e32 v97, 0, v97
	v_cndmask_b32_e64 v99, 0, 32, s[70:71]
	v_ldexp_f32 v98, v98, v99
	v_log_f32_e32 v98, v98
	v_cndmask_b32_e32 v33, v200, v33, vcc
	s_or_b64 vcc, s[2:3], s[42:43]
	v_mul_f32_e32 v99, 0x3f317217, v98
	v_fma_f32 v99, v98, s96, -v99
	v_fmac_f32_e32 v99, 0x3377d1cf, v98
	v_fmac_f32_e32 v99, 0x3f317217, v98
	v_cmp_lt_f32_e64 s[74:75], |v98|, s97
	s_nop 1
	v_cndmask_b32_e64 v98, v98, v99, s[74:75]
	v_cndmask_b32_e64 v99, 0, v199, s[70:71]
	v_sub_f32_e32 v98, v98, v99
	v_mul_f32_e64 v99, |v35|, s79
	v_exp_f32_e32 v99, v99
	v_add_f32_e32 v98, v97, v98
	v_cndmask_b32_e64 v97, 0, -v98, vcc
	v_sub_f32_e32 v34, v34, v98
	v_add_f32_e32 v99, 1.0, v99
	v_cmp_gt_f32_e64 s[70:71], s33, v99
	v_max_f32_e32 v98, v35, v35
	v_max_f32_e32 v98, 0, v98
	v_cndmask_b32_e64 v100, 0, 32, s[70:71]
	v_ldexp_f32 v99, v99, v100
	v_log_f32_e32 v99, v99
	v_cndmask_b32_e32 v34, v200, v34, vcc
	s_or_b64 vcc, s[2:3], s[44:45]
	v_mul_f32_e32 v100, 0x3f317217, v99
	v_fma_f32 v100, v99, s96, -v100
	v_fmac_f32_e32 v100, 0x3377d1cf, v99
	v_fmac_f32_e32 v100, 0x3f317217, v99
	v_cmp_lt_f32_e64 s[74:75], |v99|, s97
	s_nop 1
	v_cndmask_b32_e64 v99, v99, v100, s[74:75]
	v_cndmask_b32_e64 v100, 0, v199, s[70:71]
	v_sub_f32_e32 v99, v99, v100
	v_mul_f32_e64 v100, |v36|, s79
	v_exp_f32_e32 v100, v100
	v_add_f32_e32 v99, v98, v99
	v_cndmask_b32_e64 v98, 0, -v99, vcc
	v_sub_f32_e32 v35, v35, v99
	v_add_f32_e32 v100, 1.0, v100
	v_cmp_gt_f32_e64 s[70:71], s33, v100
	v_max_f32_e32 v99, v36, v36
	v_max_f32_e32 v99, 0, v99
	v_cndmask_b32_e64 v101, 0, 32, s[70:71]
	v_ldexp_f32 v100, v100, v101
	v_log_f32_e32 v100, v100
	v_cndmask_b32_e32 v35, v200, v35, vcc
	s_or_b64 vcc, s[2:3], s[46:47]
	v_mul_f32_e32 v101, 0x3f317217, v100
	v_fma_f32 v101, v100, s96, -v101
	v_fmac_f32_e32 v101, 0x3377d1cf, v100
	v_fmac_f32_e32 v101, 0x3f317217, v100
	v_cmp_lt_f32_e64 s[74:75], |v100|, s97
	s_nop 1
	v_cndmask_b32_e64 v100, v100, v101, s[74:75]
	v_cndmask_b32_e64 v101, 0, v199, s[70:71]
	v_sub_f32_e32 v100, v100, v101
	v_mul_f32_e64 v101, |v37|, s79
	v_exp_f32_e32 v101, v101
	v_add_f32_e32 v100, v99, v100
	v_cndmask_b32_e64 v99, 0, -v100, vcc
	v_sub_f32_e32 v36, v36, v100
	v_add_f32_e32 v101, 1.0, v101
	v_cmp_gt_f32_e64 s[70:71], s33, v101
	v_max_f32_e32 v100, v37, v37
	v_max_f32_e32 v100, 0, v100
	v_cndmask_b32_e64 v102, 0, 32, s[70:71]
	v_ldexp_f32 v101, v101, v102
	v_log_f32_e32 v101, v101
	v_cndmask_b32_e32 v36, v200, v36, vcc
	s_or_b64 vcc, s[2:3], s[48:49]
	v_mul_f32_e32 v102, 0x3f317217, v101
	v_fma_f32 v102, v101, s96, -v102
	v_fmac_f32_e32 v102, 0x3377d1cf, v101
	v_fmac_f32_e32 v102, 0x3f317217, v101
	v_cmp_lt_f32_e64 s[74:75], |v101|, s97
	s_nop 1
	v_cndmask_b32_e64 v101, v101, v102, s[74:75]
	v_cndmask_b32_e64 v102, 0, v199, s[70:71]
	v_sub_f32_e32 v101, v101, v102
	v_mul_f32_e64 v102, |v38|, s79
	v_exp_f32_e32 v102, v102
	v_add_f32_e32 v101, v100, v101
	v_cndmask_b32_e64 v100, 0, -v101, vcc
	v_sub_f32_e32 v37, v37, v101
	v_add_f32_e32 v102, 1.0, v102
; __device__ __forceinline__ float softplusf_(float z) { return fmaxf(z, 0.f) + __logf(1.f + __expf(-fabsf(z))); }
; __global__ void __launch_bounds__(NTHR, 2) fwd_kernel(Args args) {
;     ...
;                         for (int i = 0; i < 16; ++i) { const bool valid = !diag || (16 * hh + i < r); const float z = Sx[i]; const float sp = softplusf_(z);
;                             lk[i] = valid ? -sp : 0.f; Sx[i] = valid ? z - sp : -1e30f; }
	v_cmp_gt_f32_e64 s[70:71], s33, v102
	v_max_f32_e32 v101, v38, v38
	v_max_f32_e32 v101, 0, v101
	v_cndmask_b32_e64 v103, 0, 32, s[70:71]
	v_ldexp_f32 v102, v102, v103
	v_log_f32_e32 v102, v102
	v_cndmask_b32_e32 v37, v200, v37, vcc
	s_or_b64 vcc, s[2:3], s[50:51]
	v_mul_f32_e32 v103, 0x3f317217, v102
	v_fma_f32 v103, v102, s96, -v103
	v_fmac_f32_e32 v103, 0x3377d1cf, v102
	v_fmac_f32_e32 v103, 0x3f317217, v102
	v_cmp_lt_f32_e64 s[74:75], |v102|, s97
	s_nop 1
	v_cndmask_b32_e64 v102, v102, v103, s[74:75]
	v_cndmask_b32_e64 v103, 0, v199, s[70:71]
	v_sub_f32_e32 v102, v102, v103
	v_mul_f32_e64 v103, |v39|, s79
	v_exp_f32_e32 v103, v103
	v_add_f32_e32 v102, v101, v102
	v_cndmask_b32_e64 v101, 0, -v102, vcc
	v_sub_f32_e32 v38, v38, v102
	v_add_f32_e32 v103, 1.0, v103
	v_cmp_gt_f32_e64 s[70:71], s33, v103
	v_max_f32_e32 v102, v39, v39
	v_max_f32_e32 v102, 0, v102
	v_cndmask_b32_e64 v104, 0, 32, s[70:71]
	v_ldexp_f32 v103, v103, v104
	v_log_f32_e32 v103, v103
	v_cndmask_b32_e32 v38, v200, v38, vcc
	s_or_b64 vcc, s[2:3], s[52:53]
	v_mul_f32_e32 v104, 0x3f317217, v103
	v_fma_f32 v104, v103, s96, -v104
	v_fmac_f32_e32 v104, 0x3377d1cf, v103
	v_fmac_f32_e32 v104, 0x3f317217, v103
	v_cmp_lt_f32_e64 s[74:75], |v103|, s97
	s_nop 1
	v_cndmask_b32_e64 v103, v103, v104, s[74:75]
	v_cndmask_b32_e64 v104, 0, v199, s[70:71]
	v_sub_f32_e32 v103, v103, v104
	v_mul_f32_e64 v104, |v40|, s79
	v_exp_f32_e32 v104, v104
	v_add_f32_e32 v103, v102, v103
	v_cndmask_b32_e64 v102, 0, -v103, vcc
	v_sub_f32_e32 v39, v39, v103
	v_add_f32_e32 v104, 1.0, v104
	v_cmp_gt_f32_e64 s[70:71], s33, v104
	v_max_f32_e32 v103, v40, v40
	v_max_f32_e32 v103, 0, v103
	v_cndmask_b32_e64 v105, 0, 32, s[70:71]
	v_ldexp_f32 v104, v104, v105
	v_log_f32_e32 v104, v104
	v_cndmask_b32_e32 v39, v200, v39, vcc
	s_or_b64 vcc, s[2:3], s[54:55]
	v_mul_f32_e32 v105, 0x3f317217, v104
	v_fma_f32 v105, v104, s96, -v105
	v_fmac_f32_e32 v105, 0x3377d1cf, v104
	v_fmac_f32_e32 v105, 0x3f317217, v104
	v_cmp_lt_f32_e64 s[74:75], |v104|, s97
	s_nop 1
	v_cndmask_b32_e64 v104, v104, v105, s[74:75]
	v_cndmask_b32_e64 v105, 0, v199, s[70:71]
	v_sub_f32_e32 v104, v104, v105
	v_mul_f32_e64 v105, |v41|, s79
	v_exp_f32_e32 v105, v105
	v_add_f32_e32 v104, v103, v104
	v_cndmask_b32_e64 v103, 0, -v104, vcc
	v_sub_f32_e32 v40, v40, v104
	v_add_f32_e32 v105, 1.0, v105
	v_cmp_gt_f32_e64 s[70:71], s33, v105
	v_max_f32_e32 v104, v41, v41
	v_max_f32_e32 v104, 0, v104
	v_cndmask_b32_e64 v106, 0, 32, s[70:71]
	v_ldexp_f32 v105, v105, v106
	v_log_f32_e32 v105, v105
	v_cndmask_b32_e32 v40, v200, v40, vcc
	s_or_b64 vcc, s[2:3], s[56:57]
	v_mul_f32_e32 v106, 0x3f317217, v105
	v_fma_f32 v106, v105, s96, -v106
	v_fmac_f32_e32 v106, 0x3377d1cf, v105
	v_fmac_f32_e32 v106, 0x3f317217, v105
	v_cmp_lt_f32_e64 s[74:75], |v105|, s97
	s_nop 1
	v_cndmask_b32_e64 v105, v105, v106, s[74:75]
	v_cndmask_b32_e64 v106, 0, v199, s[70:71]
	v_sub_f32_e32 v105, v105, v106
	v_mul_f32_e64 v106, |v42|, s79
	v_exp_f32_e32 v106, v106
	v_add_f32_e32 v104, v104, v105
	v_cndmask_b32_e64 v105, 0, -v104, vcc
	v_sub_f32_e32 v41, v41, v104
	v_add_f32_e32 v106, 1.0, v106
	v_cmp_gt_f32_e64 s[70:71], s33, v106
	v_max_f32_e32 v104, v42, v42
	v_max_f32_e32 v104, 0, v104
	v_cndmask_b32_e64 v107, 0, 32, s[70:71]
	v_ldexp_f32 v106, v106, v107
	v_log_f32_e32 v106, v106
	v_cndmask_b32_e32 v41, v200, v41, vcc
	s_or_b64 vcc, s[2:3], s[58:59]
	v_mul_f32_e32 v107, 0x3f317217, v106
	v_fma_f32 v107, v106, s96, -v107
	v_fmac_f32_e32 v107, 0x3377d1cf, v106
	v_fmac_f32_e32 v107, 0x3f317217, v106
	v_cmp_lt_f32_e64 s[74:75], |v106|, s97
	s_nop 1
	v_cndmask_b32_e64 v106, v106, v107, s[74:75]
	v_cndmask_b32_e64 v107, 0, v199, s[70:71]
	v_sub_f32_e32 v106, v106, v107
	v_mul_f32_e64 v107, |v43|, s79
	v_exp_f32_e32 v107, v107
	v_add_f32_e32 v104, v104, v106
	v_cndmask_b32_e64 v106, 0, -v104, vcc
	v_sub_f32_e32 v42, v42, v104
	v_add_f32_e32 v107, 1.0, v107
	v_cmp_gt_f32_e64 s[70:71], s33, v107
	v_max_f32_e32 v104, v43, v43
	v_max_f32_e32 v104, 0, v104
	v_cndmask_b32_e64 v108, 0, 32, s[70:71]
	v_ldexp_f32 v107, v107, v108
	v_log_f32_e32 v107, v107
	v_cndmask_b32_e32 v42, v200, v42, vcc
	s_or_b64 vcc, s[2:3], s[60:61]
	v_mul_f32_e32 v108, 0x3f317217, v107
	v_fma_f32 v108, v107, s96, -v108
	v_fmac_f32_e32 v108, 0x3377d1cf, v107
	v_fmac_f32_e32 v108, 0x3f317217, v107
	v_cmp_lt_f32_e64 s[74:75], |v107|, s97
	s_nop 1
	v_cndmask_b32_e64 v107, v107, v108, s[74:75]
	v_cndmask_b32_e64 v108, 0, v199, s[70:71]
	v_sub_f32_e32 v107, v107, v108
	v_mul_f32_e64 v108, |v44|, s79
	v_exp_f32_e32 v108, v108
	v_add_f32_e32 v104, v104, v107
	v_cndmask_b32_e64 v107, 0, -v104, vcc
	v_sub_f32_e32 v43, v43, v104
	v_add_f32_e32 v108, 1.0, v108
	v_cmp_gt_f32_e64 s[70:71], s33, v108
	v_max_f32_e32 v104, v44, v44
	v_max_f32_e32 v104, 0, v104
	v_cndmask_b32_e64 v109, 0, 32, s[70:71]
	v_ldexp_f32 v108, v108, v109
	v_log_f32_e32 v108, v108
	v_cndmask_b32_e32 v43, v200, v43, vcc
	s_or_b64 vcc, s[2:3], s[62:63]
	v_mul_f32_e32 v109, 0x3f317217, v108
	v_fma_f32 v109, v108, s96, -v109
	v_fmac_f32_e32 v109, 0x3377d1cf, v108
	v_fmac_f32_e32 v109, 0x3f317217, v108
	v_cmp_lt_f32_e64 s[74:75], |v108|, s97
	s_nop 1
	v_cndmask_b32_e64 v108, v108, v109, s[74:75]
	v_cndmask_b32_e64 v109, 0, v199, s[70:71]
	v_sub_f32_e32 v108, v108, v109
	v_mul_f32_e64 v109, |v45|, s79
	v_exp_f32_e32 v109, v109
	v_add_f32_e32 v104, v104, v108
	v_cndmask_b32_e64 v108, 0, -v104, vcc
	v_sub_f32_e32 v44, v44, v104
	v_add_f32_e32 v109, 1.0, v109
	v_cmp_gt_f32_e64 s[70:71], s33, v109
	v_max_f32_e32 v104, v45, v45
	v_max_f32_e32 v104, 0, v104
	v_cndmask_b32_e64 v110, 0, 32, s[70:71]
	v_ldexp_f32 v109, v109, v110
	v_log_f32_e32 v109, v109
	v_cndmask_b32_e32 v44, v200, v44, vcc
; __device__ __forceinline__ unsigned pk2(float lo, float hi) { f32x2_t v = {lo, hi}; bf16x2_t b = __builtin_convertvector(v, bf16x2_t); return __builtin_bit_cast(unsigned, b); }
; __device__ __forceinline__ float shx(float v, int mask, int lane) { return __int_as_float(__builtin_amdgcn_ds_bpermute((lane ^ mask) << 2, __float_as_int(v))); }
; __global__ void __launch_bounds__(NTHR, 2) fwd_kernel(Args args) {
;     ...
;                         float ex[16], run = 0.f;
; #pragma unroll
;                         for (int i = 15; i >= 0; --i) { ex[i] = run; run += lk[i]; }
;                         const float other = shx(run, 32, lane);
;                         const float wb = R + (hh == 0 ? other : 0.f);
;                         u32x4 pw[2];
; #pragma unroll
;                         for (int q4 = 0; q4 < 4; ++q4) {
;                             const float e0 = __expf(Sx[4 * q4] + (wb + ex[4 * q4])), e1 = __expf(Sx[4 * q4 + 1] + (wb + ex[4 * q4 + 1])), e2 = __expf(Sx[4 * q4 + 2] + (wb + ex[4 * q4 + 2])), e3 = __expf(Sx[4 * q4 + 3] + (wb + ex[4 * q4 + 3]));
;                             pw[q4 >> 1][(q4 & 1) * 2] = pk2(e0, e1); pw[q4 >> 1][(q4 & 1) * 2 + 1] = pk2(e2, e3);
;                         }
;                         R += run + other;
; #pragma unroll
;                         for (int s = 0; s < 2; ++s) {
;                             const bf16x8 pa = __builtin_bit_cast(bf16x8, pw[s]);
;                             o0 = __builtin_amdgcn_mfma_f32_32x32x16_bf16(pa, va[0][s], o0, 0, 0, 0);
;                             o1 = __builtin_amdgcn_mfma_f32_32x32x16_bf16(pa, va[1][s], o1, 0, 0, 0);
;                         }
;                         if (__all(R < -104.f)) break;
	s_or_b64 vcc, s[2:3], s[64:65]
	v_mul_f32_e32 v110, 0x3f317217, v109
	v_fma_f32 v110, v109, s96, -v110
	v_fmac_f32_e32 v110, 0x3377d1cf, v109
	v_fmac_f32_e32 v110, 0x3f317217, v109
	v_cmp_lt_f32_e64 s[74:75], |v109|, s97
	s_nop 1
	v_cndmask_b32_e64 v109, v109, v110, s[74:75]
	v_cndmask_b32_e64 v110, 0, v199, s[70:71]
	v_sub_f32_e32 v109, v109, v110
	v_mul_f32_e64 v110, |v46|, s79
	v_exp_f32_e32 v110, v110
	v_add_f32_e32 v104, v104, v109
	v_cndmask_b32_e64 v109, 0, -v104, vcc
	v_sub_f32_e32 v45, v45, v104
	v_add_f32_e32 v110, 1.0, v110
	v_cmp_gt_f32_e64 s[70:71], s33, v110
	v_max_f32_e32 v104, v46, v46
	v_max_f32_e32 v104, 0, v104
	v_cndmask_b32_e64 v111, 0, 32, s[70:71]
	v_ldexp_f32 v110, v110, v111
	v_log_f32_e32 v110, v110
	v_cndmask_b32_e32 v45, v200, v45, vcc
	s_or_b64 vcc, s[2:3], s[66:67]
	v_mul_f32_e32 v111, 0x3f317217, v110
	v_fma_f32 v111, v110, s96, -v111
	v_fmac_f32_e32 v111, 0x3377d1cf, v110
	v_fmac_f32_e32 v111, 0x3f317217, v110
	v_cmp_lt_f32_e64 s[74:75], |v110|, s97
	s_nop 1
	v_cndmask_b32_e64 v110, v110, v111, s[74:75]
	v_cndmask_b32_e64 v111, 0, v199, s[70:71]
	v_sub_f32_e32 v110, v110, v111
	v_mul_f32_e64 v111, |v47|, s79
	v_exp_f32_e32 v111, v111
	v_add_f32_e32 v104, v104, v110
	v_cndmask_b32_e64 v110, 0, -v104, vcc
	v_sub_f32_e32 v46, v46, v104
	v_add_f32_e32 v111, 1.0, v111
	v_cmp_gt_f32_e64 s[70:71], s33, v111
	v_max_f32_e32 v104, v47, v47
	v_max_f32_e32 v104, 0, v104
	v_cndmask_b32_e64 v112, 0, 32, s[70:71]
	v_ldexp_f32 v111, v111, v112
	v_log_f32_e32 v111, v111
	v_cndmask_b32_e32 v46, v200, v46, vcc
	s_or_b64 vcc, s[2:3], s[68:69]
	s_mov_b32 s2, 0xc2d00000
	v_mul_f32_e32 v112, 0x3f317217, v111
	v_fma_f32 v112, v111, s96, -v112
	v_fmac_f32_e32 v112, 0x3377d1cf, v111
	v_fmac_f32_e32 v112, 0x3f317217, v111
	v_cmp_lt_f32_e64 s[74:75], |v111|, s97
	s_nop 1
	v_cndmask_b32_e64 v111, v111, v112, s[74:75]
	v_cndmask_b32_e64 v112, 0, v199, s[70:71]
	v_sub_f32_e32 v111, v111, v112
	v_add_f32_e32 v104, v104, v111
	v_sub_f32_e32 v47, v47, v104
	v_sub_f32_e32 v104, 0, v104
	v_cndmask_b32_e32 v104, 0, v104, vcc
	v_add_f32_e32 v110, v104, v110
	v_add_f32_e32 v109, v110, v109
	v_add_f32_e32 v108, v109, v108
	v_add_f32_e32 v107, v108, v107
	v_add_f32_e32 v106, v107, v106
	v_add_f32_e32 v105, v106, v105
	v_add_f32_e32 v103, v105, v103
	v_add_f32_e32 v102, v103, v102
	v_add_f32_e32 v101, v102, v101
	v_add_f32_e32 v100, v101, v100
	v_add_f32_e32 v99, v100, v99
	v_add_f32_e32 v98, v99, v98
	v_add_f32_e32 v97, v98, v97
	v_add_f32_e32 v96, v97, v96
	v_add_f32_e32 v89, v96, v89
	v_mov_b32_e32 v111, v89
	v_mov_b32_e32 v112, v89
	s_nop 1
	v_permlane32_swap_b32_e32 v111, v112
	v_cndmask_b32_e64 v111, v111, v112, s[36:37]
	v_cndmask_b32_e32 v47, v200, v47, vcc
	s_mov_b64 s[70:71], -1
	s_mov_b64 s[74:75], -1
	s_waitcnt lgkmcnt(0)
	v_cndmask_b32_e64 v112, 0, v111, s[36:37]
	v_add_f32_e32 v112, v87, v112
	v_add_f32_e32 v96, v112, v96
	v_add_f32_e32 v32, v32, v96
	v_add_f32_e32 v96, v112, v97
	v_add_f32_e32 v33, v33, v96
	v_add_f32_e32 v96, v112, v98
	v_add_f32_e32 v34, v34, v96
	v_add_f32_e32 v96, v112, v99
	v_add_f32_e32 v35, v35, v96
	v_mul_f32_e32 v32, 0x3fb8aa3b, v32
	v_mul_f32_e32 v33, 0x3fb8aa3b, v33
	v_mul_f32_e32 v34, 0x3fb8aa3b, v34
	v_mul_f32_e32 v35, 0x3fb8aa3b, v35
	v_exp_f32_e32 v32, v32
	v_exp_f32_e32 v33, v33
	v_exp_f32_e32 v34, v34
	v_exp_f32_e32 v35, v35
	v_cvt_pk_bf16_f32 v32, v32, v33
	v_cvt_pk_bf16_f32 v33, v34, v35
	v_add_f32_e32 v34, v112, v100
	v_add_f32_e32 v35, v112, v101
	v_add_f32_e32 v34, v36, v34
	v_add_f32_e32 v35, v37, v35
	v_add_f32_e32 v36, v112, v102
	v_add_f32_e32 v37, v112, v103
	v_add_f32_e32 v36, v38, v36
	v_add_f32_e32 v37, v39, v37
	v_mul_f32_e32 v34, 0x3fb8aa3b, v34
	v_mul_f32_e32 v35, 0x3fb8aa3b, v35
	v_mul_f32_e32 v36, 0x3fb8aa3b, v36
	v_mul_f32_e32 v37, 0x3fb8aa3b, v37
	v_exp_f32_e32 v34, v34
	v_exp_f32_e32 v35, v35
	v_exp_f32_e32 v36, v36
	v_exp_f32_e32 v37, v37
	v_add_f32_e32 v38, v112, v107
	v_cvt_pk_bf16_f32 v34, v34, v35
	v_add_f32_e32 v39, v112, v108
	v_cvt_pk_bf16_f32 v35, v36, v37
	v_add_f32_e32 v36, v112, v105
	v_add_f32_e32 v37, v112, v106
	v_add_f32_e32 v36, v40, v36
	v_add_f32_e32 v37, v41, v37
	v_add_f32_e32 v38, v42, v38
	v_add_f32_e32 v39, v43, v39
	v_mul_f32_e32 v36, 0x3fb8aa3b, v36
	v_mul_f32_e32 v37, 0x3fb8aa3b, v37
	v_mul_f32_e32 v38, 0x3fb8aa3b, v38
	v_mul_f32_e32 v39, 0x3fb8aa3b, v39
	v_exp_f32_e32 v36, v36
	v_exp_f32_e32 v37, v37
	v_exp_f32_e32 v38, v38
	v_exp_f32_e32 v39, v39
	v_add_f32_e32 v40, v112, v104
	v_cvt_pk_bf16_f32 v36, v36, v37
	v_add_f32_e32 v41, 0, v112
	v_cvt_pk_bf16_f32 v37, v38, v39
	v_add_f32_e32 v38, v112, v109
	v_add_f32_e32 v39, v112, v110
	v_add_f32_e32 v38, v44, v38
	v_add_f32_e32 v39, v45, v39
	v_add_f32_e32 v40, v46, v40
	v_add_f32_e32 v41, v47, v41
	v_mul_f32_e32 v38, 0x3fb8aa3b, v38
	v_mul_f32_e32 v39, 0x3fb8aa3b, v39
	v_mul_f32_e32 v40, 0x3fb8aa3b, v40
	v_mul_f32_e32 v41, 0x3fb8aa3b, v41
	v_exp_f32_e32 v38, v38
	v_exp_f32_e32 v39, v39
	v_exp_f32_e32 v40, v40
	v_exp_f32_e32 v41, v41
	v_mfma_f32_32x32x16_bf16 v[0:15], v[32:35], v[76:79], v[0:15]
	v_cvt_pk_bf16_f32 v38, v38, v39
	v_cvt_pk_bf16_f32 v39, v40, v41
	v_add_f32_e32 v40, v89, v111
	v_add_f32_e32 v87, v87, v40
	v_cmp_gt_f32_e32 vcc, s2, v87
	s_cmp_lg_u64 vcc, exec
	v_mfma_f32_32x32x16_bf16 v[16:31], v[32:35], v[72:75], v[16:31]
	v_mfma_f32_32x32x16_bf16 v[0:15], v[36:39], v[68:71], v[0:15]
	v_mfma_f32_32x32x16_bf16 v[16:31], v[36:39], v[64:67], v[16:31]
	s_cbranch_scc0 .LBB0_173
	s_max_u32 s2, s23, 2
	s_lshl_b32 s2, s2, 5
	s_sub_i32 s2, s2, 64
	s_ashr_i32 s3, s2, 31
	s_add_i32 s23, s23, -1
	s_add_i32 s4, s4, 1
	s_cmp_eq_u32 s23, -1
	s_mov_b64 s[70:71], 0
	s_cselect_b64 s[74:75], -1, 0
